# v045 + scan loaders poll the prep-completion counter at chunk 60 (last safe point) instead of 56
# speedup vs baseline: 1.0035x; 1.0035x over previous
; __device__ __forceinline__ unsigned xb_ld(unsigned* p)              { return __hip_atomic_load(p, __ATOMIC_RELAXED, __HIP_MEMORY_SCOPE_AGENT); }
; __device__ __forceinline__ void scan_item(LAS unsigned char* lds, const ScanPtrs& P, bf16* YC, int item, unsigned* half_cnt, unsigned half_expect) {
;     ...
;             if (c == NCH / 4 - 8) {
;                 unsigned sp_ = 0u; while (xb_ld(half_cnt) < half_expect) { __builtin_amdgcn_s_sleep(8); if (++sp_ > (1u << 20)) break; }
;                 __builtin_amdgcn_fence(__ATOMIC_ACQUIRE, "agent"); asm volatile("s_waitcnt vmcnt(0)" ::: "memory"); }
.LBB0_742:
	s_cmp_lg_u32 s25, 60
	s_cbranch_scc1 .LBB0_757
	s_mov_b32 s0, 0x100000
	s_branch .LBB0_746
